# RG-LRU task prologue: gate-weight load batches merged into two groups per pass (later batches use their own temporaries), one exposed load latency per group
# speedup vs baseline: 1.0023x; 1.0023x over previous
.LBB0_200:
	s_or_b64 exec, exec, s[80:81]
	v_readfirstlane_b32 s1, v0
	s_cmpk_gt_u32 s1, 0xff
	s_mov_b64 s[80:81], -1
	s_cbranch_scc1 .LBB0_195
	s_and_b32 s0, s45, 7
	s_lshl_b32 s0, s0, 8
	s_or_b32 s1, s1, s0
	s_bfe_u32 s0, s1, 0x30005
	s_lshl_b32 s20, s0, 8
	v_lshl_add_u64 v[24:25], v[144:145], 0, s[20:21]
	v_lshl_add_u64 v[20:21], v[146:147], 0, s[20:21]
	s_lshl_b32 s20, s0, 14
	v_lshl_add_u64 v[44:45], v[148:149], 0, s[20:21]
	v_mov_b32_e32 v161, v99
	v_lshl_add_u64 v[68:69], v[44:45], 0, v[160:161]
	global_load_dword v40, v[68:69], off offset:256
	global_load_dword v41, v[68:69], off
	global_load_dwordx4 v[0:3], v[24:25], off offset:16
	global_load_dwordx4 v[4:7], v[24:25], off
	global_load_dwordx4 v[8:11], v[24:25], off offset:2064
	global_load_dwordx4 v[12:15], v[24:25], off offset:2048
	v_add_co_u32_e32 v32, vcc, 0x1000, v24
	s_mov_b64 s[22:23], 0x1800
	v_lshl_add_u64 v[28:29], v[24:25], 0, s[54:55]
	v_lshl_add_u64 v[36:37], v[24:25], 0, s[22:23]
	v_addc_co_u32_e32 v33, vcc, 0, v25, vcc
	global_load_dwordx4 v[16:19], v[20:21], off offset:16
	s_nop 0
	global_load_dwordx4 v[20:23], v[20:21], off
	s_nop 0
	global_load_dwordx4 v[24:27], v[32:33], off
	s_nop 0
	global_load_dwordx4 v[28:31], v[28:29], off offset:16
	s_nop 0
	global_load_dwordx4 v[32:35], v[32:33], off offset:2048
	s_nop 0
	global_load_dwordx4 v[36:39], v[36:37], off offset:16
	v_mov_b32_e32 v163, v99
	v_lshl_add_u64 v[72:73], v[44:45], 0, v[162:163]
	v_lshl_add_u64 v[76:77], v[150:151], 0, s[20:21]
	v_lshl_add_u64 v[104:105], v[76:77], 0, v[160:161]
	s_waitcnt vmcnt(0)
	v_lshl_add_u64 v[108:109], v[76:77], 0, v[162:163]
	s_lshl_b32 s26, s0, 6
	s_lshr_b32 s23, s1, 8
	s_lshl_b32 s1, s1, 7
	s_and_b32 s22, s1, 0xf80
	s_lshl_b32 s1, s23, 12
	s_or_b32 s20, s22, s1
	s_add_u32 s80, s20, -3
	s_addc_u32 s81, 0, -1
	v_cmp_gt_i32_e32 vcc, s22, v172
	v_mov_b32_e32 v110, v99
	v_mov_b32_e32 v111, v99
	s_waitcnt vmcnt(10)
	v_cvt_pk_bf16_f32 v40, v41, v40
	global_load_dword v41, v[68:69], off offset:768
	global_load_dword v234, v[68:69], off offset:512
	global_load_dword v42, v[68:69], off offset:1280
	global_load_dword v235, v[68:69], off offset:1024
	global_load_dword v43, v[68:69], off offset:1792
	global_load_dword v236, v[68:69], off offset:1536
	global_load_dword v44, v[72:73], off offset:256
	global_load_dword v237, v[72:73], off
	global_load_dword v45, v[72:73], off offset:768
	global_load_dword v238, v[72:73], off offset:512
	global_load_dword v46, v[72:73], off offset:1280
	global_load_dword v239, v[72:73], off offset:1024
	global_load_dword v47, v[72:73], off offset:1792
	global_load_dword v240, v[72:73], off offset:1536
	global_load_dword v48, v[68:69], off offset:320
	global_load_dword v241, v[68:69], off offset:64
	global_load_dword v49, v[68:69], off offset:832
	global_load_dword v242, v[68:69], off offset:576
	global_load_dword v50, v[68:69], off offset:1344
	global_load_dword v243, v[68:69], off offset:1088
	global_load_dword v51, v[68:69], off offset:1856
	global_load_dword v244, v[68:69], off offset:1600
	global_load_dword v52, v[72:73], off offset:320
	global_load_dword v245, v[72:73], off offset:64
	global_load_dword v53, v[72:73], off offset:832
	global_load_dword v246, v[72:73], off offset:576
	global_load_dword v54, v[72:73], off offset:1344
	global_load_dword v247, v[72:73], off offset:1088
	global_load_dword v55, v[72:73], off offset:1856
	global_load_dword v248, v[72:73], off offset:1600
	global_load_dword v56, v[68:69], off offset:384
	global_load_dword v249, v[68:69], off offset:128
	global_load_dword v57, v[68:69], off offset:896
	global_load_dword v250, v[68:69], off offset:640
	global_load_dword v58, v[68:69], off offset:1408
	global_load_dword v251, v[68:69], off offset:1152
	global_load_dword v59, v[68:69], off offset:1920
	global_load_dword v252, v[68:69], off offset:1664
	global_load_dword v60, v[72:73], off offset:384
	global_load_dword v253, v[72:73], off offset:128
	global_load_dword v61, v[72:73], off offset:896
	global_load_dword v135, v[72:73], off offset:640
	global_load_dword v62, v[72:73], off offset:1408
	global_load_dword v136, v[72:73], off offset:1152
	global_load_dword v63, v[72:73], off offset:1920
	global_load_dword v137, v[72:73], off offset:1664
	global_load_dword v64, v[68:69], off offset:448
	global_load_dword v138, v[68:69], off offset:192
	global_load_dword v65, v[68:69], off offset:960
	global_load_dword v139, v[68:69], off offset:704
	global_load_dword v66, v[68:69], off offset:1472
	global_load_dword v140, v[68:69], off offset:1216
	global_load_dword v67, v[68:69], off offset:1984
	s_nop 0
	global_load_dword v141, v[68:69], off offset:1728
	global_load_dword v68, v[72:73], off offset:448
	global_load_dword v142, v[72:73], off offset:192
	global_load_dword v69, v[72:73], off offset:960
	global_load_dword v143, v[72:73], off offset:704
	global_load_dword v70, v[72:73], off offset:1472
	global_load_dword v165, v[72:73], off offset:1216
	global_load_dword v71, v[72:73], off offset:1984
	s_nop 0
	global_load_dword v168, v[72:73], off offset:1728
	global_load_dword v72, v[104:105], off offset:256
	global_load_dword v170, v[104:105], off
	global_load_dword v73, v[104:105], off offset:768
	global_load_dword v171, v[104:105], off offset:512
	global_load_dword v74, v[104:105], off offset:1280
	global_load_dword v222, v[104:105], off offset:1024
	global_load_dword v75, v[104:105], off offset:1792
	global_load_dword v223, v[104:105], off offset:1536
	global_load_dword v76, v[108:109], off offset:256
	global_load_dword v224, v[108:109], off
	global_load_dword v77, v[108:109], off offset:768
	global_load_dword v225, v[108:109], off offset:512
	global_load_dword v78, v[108:109], off offset:1280
	global_load_dword v226, v[108:109], off offset:1024
	global_load_dword v79, v[108:109], off offset:1792
	global_load_dword v227, v[108:109], off offset:1536
	global_load_dword v80, v[104:105], off offset:320
	global_load_dword v228, v[104:105], off offset:64
	s_waitcnt vmcnt(0)
	v_cvt_pk_bf16_f32 v41, v234, v41
	v_cvt_pk_bf16_f32 v42, v235, v42
	v_cvt_pk_bf16_f32 v43, v236, v43
	v_cvt_pk_bf16_f32 v44, v237, v44
	v_cvt_pk_bf16_f32 v45, v238, v45
	v_cvt_pk_bf16_f32 v46, v239, v46
	v_cvt_pk_bf16_f32 v47, v240, v47
	v_cvt_pk_bf16_f32 v48, v241, v48
	v_cvt_pk_bf16_f32 v49, v242, v49
	v_cvt_pk_bf16_f32 v50, v243, v50
	v_cvt_pk_bf16_f32 v51, v244, v51
	v_cvt_pk_bf16_f32 v52, v245, v52
	v_cvt_pk_bf16_f32 v53, v246, v53
	v_cvt_pk_bf16_f32 v54, v247, v54
	v_cvt_pk_bf16_f32 v55, v248, v55
	v_cvt_pk_bf16_f32 v56, v249, v56
	v_cvt_pk_bf16_f32 v57, v250, v57
	v_cvt_pk_bf16_f32 v58, v251, v58
	v_cvt_pk_bf16_f32 v59, v252, v59
	v_cvt_pk_bf16_f32 v60, v253, v60
	v_cvt_pk_bf16_f32 v61, v135, v61
	v_cvt_pk_bf16_f32 v62, v136, v62
	v_cvt_pk_bf16_f32 v63, v137, v63
	v_cvt_pk_bf16_f32 v64, v138, v64
	v_cvt_pk_bf16_f32 v65, v139, v65
	v_cvt_pk_bf16_f32 v66, v140, v66
	v_cvt_pk_bf16_f32 v67, v141, v67
	v_cvt_pk_bf16_f32 v68, v142, v68
	v_cvt_pk_bf16_f32 v69, v143, v69
	v_cvt_pk_bf16_f32 v70, v165, v70
	v_cvt_pk_bf16_f32 v71, v168, v71
	v_cvt_pk_bf16_f32 v72, v170, v72
	v_cvt_pk_bf16_f32 v73, v171, v73
	v_cvt_pk_bf16_f32 v74, v222, v74
	v_cvt_pk_bf16_f32 v75, v223, v75
	v_cvt_pk_bf16_f32 v76, v224, v76
	v_cvt_pk_bf16_f32 v77, v225, v77
	v_cvt_pk_bf16_f32 v78, v226, v78
	v_cvt_pk_bf16_f32 v79, v227, v79
	v_cvt_pk_bf16_f32 v80, v228, v80
	global_load_dword v81, v[104:105], off offset:832
	global_load_dword v234, v[104:105], off offset:576
	global_load_dword v82, v[104:105], off offset:1344
	global_load_dword v235, v[104:105], off offset:1088
	global_load_dword v83, v[104:105], off offset:1856
	global_load_dword v236, v[104:105], off offset:1600
	global_load_dword v84, v[108:109], off offset:320
	global_load_dword v237, v[108:109], off offset:64
	global_load_dword v85, v[108:109], off offset:832
	global_load_dword v238, v[108:109], off offset:576
	global_load_dword v86, v[108:109], off offset:1344
	global_load_dword v239, v[108:109], off offset:1088
	global_load_dword v87, v[108:109], off offset:1856
	global_load_dword v240, v[108:109], off offset:1600
	global_load_dword v88, v[104:105], off offset:384
	global_load_dword v241, v[104:105], off offset:128
	global_load_dword v89, v[104:105], off offset:896
	global_load_dword v242, v[104:105], off offset:640
	global_load_dword v90, v[104:105], off offset:1408
	global_load_dword v243, v[104:105], off offset:1152
	global_load_dword v91, v[104:105], off offset:1920
	global_load_dword v244, v[104:105], off offset:1664
	global_load_dword v92, v[108:109], off offset:384
	global_load_dword v245, v[108:109], off offset:128
	global_load_dword v93, v[108:109], off offset:896
	global_load_dword v246, v[108:109], off offset:640
	global_load_dword v94, v[108:109], off offset:1408
	global_load_dword v247, v[108:109], off offset:1152
	global_load_dword v95, v[108:109], off offset:1920
	global_load_dword v248, v[108:109], off offset:1664
	global_load_dword v249, v[104:105], off offset:448
	global_load_dword v100, v[104:105], off offset:192
	global_load_dword v250, v[104:105], off offset:960
	global_load_dword v101, v[104:105], off offset:704
	global_load_dword v251, v[104:105], off offset:1472
	global_load_dword v102, v[104:105], off offset:1216
	global_load_dword v252, v[104:105], off offset:1984
	global_load_dword v103, v[104:105], off offset:1728
	global_load_dword v253, v[108:109], off offset:448
	global_load_dword v104, v[108:109], off offset:192
	global_load_dword v135, v[108:109], off offset:960
	global_load_dword v105, v[108:109], off offset:704
	global_load_dword v136, v[108:109], off offset:1472
	global_load_dword v106, v[108:109], off offset:1216
	global_load_dword v137, v[108:109], off offset:1984
	global_load_dword v107, v[108:109], off offset:1728
	v_or_b32_e32 v108, s26, v97
	v_lshlrev_b32_e32 v108, 2, v108
	v_mov_b32_e32 v109, v99
	s_waitcnt vmcnt(0)
	v_cvt_pk_bf16_f32 v81, v234, v81
	v_cvt_pk_bf16_f32 v82, v235, v82
	v_cvt_pk_bf16_f32 v83, v236, v83
	v_cvt_pk_bf16_f32 v84, v237, v84
	v_cvt_pk_bf16_f32 v85, v238, v85
	v_cvt_pk_bf16_f32 v86, v239, v86
	v_cvt_pk_bf16_f32 v87, v240, v87
	v_cvt_pk_bf16_f32 v88, v241, v88
	v_cvt_pk_bf16_f32 v89, v242, v89
	v_cvt_pk_bf16_f32 v90, v243, v90
	v_cvt_pk_bf16_f32 v91, v244, v91
	v_cvt_pk_bf16_f32 v92, v245, v92
	v_cvt_pk_bf16_f32 v93, v246, v93
	v_cvt_pk_bf16_f32 v94, v247, v94
	v_cvt_pk_bf16_f32 v95, v248, v95
	v_cvt_pk_bf16_f32 v100, v100, v249
	v_cvt_pk_bf16_f32 v101, v101, v250
	v_cvt_pk_bf16_f32 v102, v102, v251
	v_cvt_pk_bf16_f32 v103, v103, v252
	v_cvt_pk_bf16_f32 v104, v104, v253
	v_cvt_pk_bf16_f32 v105, v105, v135
	v_cvt_pk_bf16_f32 v106, v106, v136
	v_cvt_pk_bf16_f32 v107, v107, v137
	global_load_dword v161, v108, s[74:75]
	global_load_dword v163, v108, s[76:77]
	global_load_dword v181, v108, s[74:75] offset:64
	global_load_dword v188, v108, s[76:77] offset:64
	global_load_dword v189, v108, s[74:75] offset:128
	global_load_dword v190, v108, s[76:77] offset:128
	global_load_dword v191, v108, s[76:77] offset:192
	global_load_dword v192, v108, s[74:75] offset:192
	global_load_dword v123, v108, s[78:79]
	global_load_dword v122, v108, s[78:79] offset:64
	global_load_dword v121, v108, s[78:79] offset:128
	global_load_dword v120, v108, s[78:79] offset:192
	v_mov_b32_e32 v108, v99
	v_lshlrev_b32_e32 v98, 1, v96
	s_and_saveexec_b64 s[82:83], vcc
	s_cbranch_execz .LBB0_203
	v_lshl_add_u64 v[108:109], s[80:81], 0, v[152:153]
	v_mov_b64_e32 v[110:111], s[16:17]
	v_mad_u64_u32 v[110:111], s[42:43], v108, s99, v[110:111]
	v_mad_i32_i24 v111, v109, s99, v111
	s_lshl_b32 s20, s26, 1
	v_lshl_add_u64 v[108:109], v[110:111], 0, s[20:21]
	v_lshl_add_u64 v[108:109], v[108:109], 0, v[98:99]
	global_load_dwordx4 v[108:111], v[108:109], off offset:3072

.LBB0_250:
	s_bfe_u32 s0, s23, 0x30005
	s_lshl_b32 s20, s0, 8
	v_lshl_add_u64 v[24:25], v[96:97], 0, s[20:21]
	v_lshl_add_u64 v[20:21], v[152:153], 0, s[20:21]
	s_lshl_b32 s20, s0, 14
	v_lshl_add_u64 v[44:45], v[154:155], 0, s[20:21]
	v_mov_b32_e32 v173, v99
	v_lshl_add_u64 v[68:69], v[44:45], 0, v[172:173]
	global_load_dword v40, v[68:69], off offset:256
	global_load_dword v41, v[68:69], off
	global_load_dwordx4 v[0:3], v[24:25], off offset:16
	global_load_dwordx4 v[4:7], v[24:25], off
	global_load_dwordx4 v[8:11], v[24:25], off offset:2064
	global_load_dwordx4 v[12:15], v[24:25], off offset:2048
	v_add_co_u32_e32 v32, vcc, 0x1000, v24
	s_mov_b64 s[26:27], 0x1800
	v_lshl_add_u64 v[28:29], v[24:25], 0, s[54:55]
	v_lshl_add_u64 v[36:37], v[24:25], 0, s[26:27]
	v_addc_co_u32_e32 v33, vcc, 0, v25, vcc
	global_load_dwordx4 v[16:19], v[20:21], off offset:16
	s_nop 0
	global_load_dwordx4 v[20:23], v[20:21], off
	s_nop 0
	global_load_dwordx4 v[24:27], v[32:33], off
	s_nop 0
	global_load_dwordx4 v[28:31], v[28:29], off offset:16
	s_nop 0
	global_load_dwordx4 v[32:35], v[32:33], off offset:2048
	s_nop 0
	global_load_dwordx4 v[36:39], v[36:37], off offset:16
	v_mov_b32_e32 v175, v99
	v_lshl_add_u64 v[72:73], v[44:45], 0, v[174:175]
	v_lshl_add_u64 v[76:77], v[156:157], 0, s[20:21]
	v_lshl_add_u64 v[104:105], v[76:77], 0, v[172:173]
	s_waitcnt vmcnt(0)
	v_lshl_add_u64 v[108:109], v[76:77], 0, v[174:175]
	s_lshl_b32 s1, s0, 6
	s_lshr_b32 s0, s23, 5
	s_ashr_i32 s72, s23, 8
	s_and_b32 s20, s23, 31
	s_cmp_eq_u32 s20, 0
	v_cvt_pk_bf16_f32 v40, v41, v40
	global_load_dword v41, v[68:69], off offset:768
	global_load_dword v252, v[68:69], off offset:512
	global_load_dword v42, v[68:69], off offset:1280
	global_load_dword v253, v[68:69], off offset:1024
	global_load_dword v43, v[68:69], off offset:1792
	global_load_dword v230, v[68:69], off offset:1536
	global_load_dword v44, v[72:73], off offset:256
	global_load_dword v231, v[72:73], off
	global_load_dword v45, v[72:73], off offset:768
	global_load_dword v232, v[72:73], off offset:512
	global_load_dword v46, v[72:73], off offset:1280
	global_load_dword v233, v[72:73], off offset:1024
	global_load_dword v47, v[72:73], off offset:1792
	global_load_dword v234, v[72:73], off offset:1536
	global_load_dword v48, v[68:69], off offset:320
	global_load_dword v235, v[68:69], off offset:64
	global_load_dword v49, v[68:69], off offset:832
	global_load_dword v120, v[68:69], off offset:576
	global_load_dword v50, v[68:69], off offset:1344
	global_load_dword v121, v[68:69], off offset:1088
	global_load_dword v51, v[68:69], off offset:1856
	global_load_dword v122, v[68:69], off offset:1600
	global_load_dword v52, v[72:73], off offset:320
	global_load_dword v123, v[72:73], off offset:64
	global_load_dword v53, v[72:73], off offset:832
	global_load_dword v143, v[72:73], off offset:576
	global_load_dword v54, v[72:73], off offset:1344
	global_load_dword v144, v[72:73], off offset:1088
	global_load_dword v55, v[72:73], off offset:1856
	global_load_dword v137, v[72:73], off offset:1600
	global_load_dword v56, v[68:69], off offset:384
	global_load_dword v138, v[68:69], off offset:128
	global_load_dword v57, v[68:69], off offset:896
	global_load_dword v139, v[68:69], off offset:640
	global_load_dword v58, v[68:69], off offset:1408
	global_load_dword v140, v[68:69], off offset:1152
	global_load_dword v59, v[68:69], off offset:1920
	global_load_dword v141, v[68:69], off offset:1664
	global_load_dword v60, v[72:73], off offset:384
	global_load_dword v142, v[72:73], off offset:128
	global_load_dword v61, v[72:73], off offset:896
	global_load_dword v133, v[72:73], off offset:640
	global_load_dword v62, v[72:73], off offset:1408
	global_load_dword v134, v[72:73], off offset:1152
	global_load_dword v63, v[72:73], off offset:1920
	global_load_dword v135, v[72:73], off offset:1664
	global_load_dword v64, v[68:69], off offset:448
	global_load_dword v136, v[68:69], off offset:192
	global_load_dword v65, v[68:69], off offset:960
	global_load_dword v239, v[68:69], off offset:704
	global_load_dword v66, v[68:69], off offset:1472
	global_load_dword v240, v[68:69], off offset:1216
	global_load_dword v67, v[68:69], off offset:1984
	s_nop 0
	global_load_dword v149, v[68:69], off offset:1728
	global_load_dword v68, v[72:73], off offset:448
	global_load_dword v150, v[72:73], off offset:192
	global_load_dword v69, v[72:73], off offset:960
	global_load_dword v151, v[72:73], off offset:704
	global_load_dword v70, v[72:73], off offset:1472
	global_load_dword v236, v[72:73], off offset:1216
	global_load_dword v71, v[72:73], off offset:1984
	s_nop 0
	global_load_dword v237, v[72:73], off offset:1728
	global_load_dword v72, v[104:105], off offset:256
	global_load_dword v238, v[104:105], off
	global_load_dword v73, v[104:105], off offset:768
	global_load_dword v145, v[104:105], off offset:512
	global_load_dword v74, v[104:105], off offset:1280
	global_load_dword v146, v[104:105], off offset:1024
	global_load_dword v75, v[104:105], off offset:1792
	global_load_dword v147, v[104:105], off offset:1536
	global_load_dword v76, v[108:109], off offset:256
	global_load_dword v148, v[108:109], off
	s_waitcnt vmcnt(0)
	v_cvt_pk_bf16_f32 v41, v252, v41
	v_cvt_pk_bf16_f32 v42, v253, v42
	v_cvt_pk_bf16_f32 v43, v230, v43
	v_cvt_pk_bf16_f32 v44, v231, v44
	v_cvt_pk_bf16_f32 v45, v232, v45
	v_cvt_pk_bf16_f32 v46, v233, v46
	v_cvt_pk_bf16_f32 v47, v234, v47
	v_cvt_pk_bf16_f32 v48, v235, v48
	v_cvt_pk_bf16_f32 v49, v120, v49
	v_cvt_pk_bf16_f32 v50, v121, v50
	v_cvt_pk_bf16_f32 v51, v122, v51
	v_cvt_pk_bf16_f32 v52, v123, v52
	v_cvt_pk_bf16_f32 v53, v143, v53
	v_cvt_pk_bf16_f32 v54, v144, v54
	v_cvt_pk_bf16_f32 v55, v137, v55
	v_cvt_pk_bf16_f32 v56, v138, v56
	v_cvt_pk_bf16_f32 v57, v139, v57
	v_cvt_pk_bf16_f32 v58, v140, v58
	v_cvt_pk_bf16_f32 v59, v141, v59
	v_cvt_pk_bf16_f32 v60, v142, v60
	v_cvt_pk_bf16_f32 v61, v133, v61
	v_cvt_pk_bf16_f32 v62, v134, v62
	v_cvt_pk_bf16_f32 v63, v135, v63
	v_cvt_pk_bf16_f32 v64, v136, v64
	v_cvt_pk_bf16_f32 v65, v239, v65
	v_cvt_pk_bf16_f32 v66, v240, v66
	v_cvt_pk_bf16_f32 v67, v149, v67
	v_cvt_pk_bf16_f32 v68, v150, v68
	v_cvt_pk_bf16_f32 v69, v151, v69
	v_cvt_pk_bf16_f32 v70, v236, v70
	v_cvt_pk_bf16_f32 v71, v237, v71
	v_cvt_pk_bf16_f32 v72, v238, v72
	v_cvt_pk_bf16_f32 v73, v145, v73
	v_cvt_pk_bf16_f32 v74, v146, v74
	v_cvt_pk_bf16_f32 v75, v147, v75
	v_cvt_pk_bf16_f32 v76, v148, v76
	global_load_dword v77, v[108:109], off offset:768
	global_load_dword v252, v[108:109], off offset:512
	global_load_dword v78, v[108:109], off offset:1280
	global_load_dword v253, v[108:109], off offset:1024
	global_load_dword v79, v[108:109], off offset:1792
	global_load_dword v230, v[108:109], off offset:1536
	global_load_dword v80, v[104:105], off offset:320
	global_load_dword v231, v[104:105], off offset:64
	global_load_dword v81, v[104:105], off offset:832
	global_load_dword v232, v[104:105], off offset:576
	global_load_dword v82, v[104:105], off offset:1344
	global_load_dword v233, v[104:105], off offset:1088
	global_load_dword v83, v[104:105], off offset:1856
	global_load_dword v234, v[104:105], off offset:1600
	global_load_dword v84, v[108:109], off offset:320
	global_load_dword v235, v[108:109], off offset:64
	global_load_dword v85, v[108:109], off offset:832
	global_load_dword v120, v[108:109], off offset:576
	global_load_dword v86, v[108:109], off offset:1344
	global_load_dword v121, v[108:109], off offset:1088
	global_load_dword v87, v[108:109], off offset:1856
	global_load_dword v122, v[108:109], off offset:1600
	global_load_dword v88, v[104:105], off offset:384
	global_load_dword v123, v[104:105], off offset:128
	global_load_dword v89, v[104:105], off offset:896
	global_load_dword v143, v[104:105], off offset:640
	global_load_dword v90, v[104:105], off offset:1408
	global_load_dword v144, v[104:105], off offset:1152
	global_load_dword v91, v[104:105], off offset:1920
	global_load_dword v137, v[104:105], off offset:1664
	global_load_dword v92, v[108:109], off offset:384
	global_load_dword v138, v[108:109], off offset:128
	global_load_dword v93, v[108:109], off offset:896
	global_load_dword v139, v[108:109], off offset:640
	global_load_dword v94, v[108:109], off offset:1408
	global_load_dword v140, v[108:109], off offset:1152
	global_load_dword v95, v[108:109], off offset:1920
	global_load_dword v141, v[108:109], off offset:1664
	global_load_dword v100, v[104:105], off offset:448
	global_load_dword v142, v[104:105], off offset:192
	global_load_dword v101, v[104:105], off offset:960
	global_load_dword v133, v[104:105], off offset:704
	global_load_dword v102, v[104:105], off offset:1472
	global_load_dword v134, v[104:105], off offset:1216
	global_load_dword v103, v[104:105], off offset:1984
	s_nop 0
	global_load_dword v135, v[104:105], off offset:1728
	global_load_dword v104, v[108:109], off offset:448
	global_load_dword v136, v[108:109], off offset:192
	global_load_dword v105, v[108:109], off offset:960
	global_load_dword v146, v[108:109], off offset:704
	global_load_dword v106, v[108:109], off offset:1472
	global_load_dword v147, v[108:109], off offset:1216
	global_load_dword v107, v[108:109], off offset:1984
	s_nop 0
	global_load_dword v145, v[108:109], off offset:1728
	v_or_b32_e32 v109, s1, v220
	v_lshlrev_b32_e32 v109, 2, v109
	s_waitcnt vmcnt(0)
	v_cvt_pk_bf16_f32 v77, v252, v77
	v_cvt_pk_bf16_f32 v78, v253, v78
	v_cvt_pk_bf16_f32 v79, v230, v79
	v_cvt_pk_bf16_f32 v80, v231, v80
	v_cvt_pk_bf16_f32 v81, v232, v81
	v_cvt_pk_bf16_f32 v82, v233, v82
	v_cvt_pk_bf16_f32 v83, v234, v83
	v_cvt_pk_bf16_f32 v84, v235, v84
	v_cvt_pk_bf16_f32 v85, v120, v85
	v_cvt_pk_bf16_f32 v86, v121, v86
	v_cvt_pk_bf16_f32 v87, v122, v87
	v_cvt_pk_bf16_f32 v88, v123, v88
	v_cvt_pk_bf16_f32 v89, v143, v89
	v_cvt_pk_bf16_f32 v90, v144, v90
	v_cvt_pk_bf16_f32 v91, v137, v91
	v_cvt_pk_bf16_f32 v92, v138, v92
	v_cvt_pk_bf16_f32 v93, v139, v93
	v_cvt_pk_bf16_f32 v94, v140, v94
	v_cvt_pk_bf16_f32 v95, v141, v95
	v_cvt_pk_bf16_f32 v100, v142, v100
	v_cvt_pk_bf16_f32 v101, v133, v101
	v_cvt_pk_bf16_f32 v102, v134, v102
	v_cvt_pk_bf16_f32 v103, v135, v103
	v_cvt_pk_bf16_f32 v104, v136, v104
	v_cvt_pk_bf16_f32 v105, v146, v105
	v_cvt_pk_bf16_f32 v106, v147, v106
	v_cvt_pk_bf16_f32 v107, v145, v107
	global_load_dword v173, v109, s[8:9]
	global_load_dword v175, v109, s[68:69]
	global_load_dword v230, v109, s[8:9] offset:64
	global_load_dword v231, v109, s[68:69] offset:64
	global_load_dword v232, v109, s[8:9] offset:128
	global_load_dword v233, v109, s[68:69] offset:128
	global_load_dword v234, v109, s[68:69] offset:192
	global_load_dword v235, v109, s[8:9] offset:192
	global_load_dword v123, v109, s[70:71]
	global_load_dword v122, v109, s[70:71] offset:64
	global_load_dword v121, v109, s[70:71] offset:128
	global_load_dword v120, v109, s[70:71] offset:192
	s_cbranch_scc1 .LBB0_267
	s_and_b32 s26, s0, 7
	s_lshl_b32 s27, s72, 3
	s_or_b32 s26, s27, s26
	s_ashr_i32 s27, s26, 31
	s_lshl_b64 s[26:27], s[26:27], 14
	v_lshl_add_u64 v[108:109], v[164:165], 0, s[26:27]
	s_mov_b32 s26, 0
	v_mov_b32_e32 v177, 0
	s_branch .LBB0_253
